# exact-split emit of the selection: per-lane count of selected keys done in blocks of 8 compares + 8 carry adds on eight mask registers (was 64 compare-wait-add triples on one)
# speedup vs baseline: 1.0092x; 1.0017x over previous
; __device__ __forceinline__ void select_group(unsigned char* ws, int r0, const bf16_t* __restrict__ kib, int n, float* sc, SelPre& pre, int nr0, const bf16_t* __restrict__ nkib, int nn) {
;     ...
;       int myc = 0;
; #pragma unroll
;       for (int i = 0; i < 64; ++i) myc += (x[i] >= tau2) ? 1 : 0;
;       int incl = myc;
; #pragma unroll
;       for (int d = 1; d < 64; d <<= 1) {
;         const int t = __shfl_up(incl, d);
;         incl += (lane >= d) ? t : 0;
;       }
;       int pos = incl - myc;
.LBB0_3246:
	s_and_b64 vcc, exec, s[0:1]
	s_cbranch_vccz .LBB0_3389
	v_mov_b32_e32 v16, v17
	v_cmp_le_u32_e64 s[38:39], s8, v238
	v_cmp_le_u32_e64 s[42:43], s8, v237
	v_cmp_le_u32_e64 s[62:63], s8, v236
	v_cmp_le_u32_e64 s[64:65], s8, v235
	v_cmp_le_u32_e64 s[66:67], s8, v234
	v_cmp_le_u32_e64 s[68:69], s8, v233
	v_cmp_le_u32_e64 s[70:71], s8, v231
	v_cmp_le_u32_e64 s[72:73], s8, v232
	v_addc_co_u32_e64 v16, s[38:39], 0, v16, s[38:39]
	v_addc_co_u32_e64 v16, s[42:43], 0, v16, s[42:43]
	v_addc_co_u32_e64 v16, s[62:63], 0, v16, s[62:63]
	v_addc_co_u32_e64 v16, s[64:65], 0, v16, s[64:65]
	v_addc_co_u32_e64 v16, s[66:67], 0, v16, s[66:67]
	v_addc_co_u32_e64 v16, s[68:69], 0, v16, s[68:69]
	v_addc_co_u32_e64 v16, s[70:71], 0, v16, s[70:71]
	v_addc_co_u32_e64 v16, s[72:73], 0, v16, s[72:73]
	v_cmp_le_u32_e64 s[38:39], s8, v230
	v_cmp_le_u32_e64 s[42:43], s8, v229
	v_cmp_le_u32_e64 s[62:63], s8, v228
	v_cmp_le_u32_e64 s[64:65], s8, v227
	v_cmp_le_u32_e64 s[66:67], s8, v226
	v_cmp_le_u32_e64 s[68:69], s8, v225
	v_cmp_le_u32_e64 s[70:71], s8, v223
	v_cmp_le_u32_e64 s[72:73], s8, v224
	v_addc_co_u32_e64 v16, s[38:39], 0, v16, s[38:39]
	v_addc_co_u32_e64 v16, s[42:43], 0, v16, s[42:43]
	v_addc_co_u32_e64 v16, s[62:63], 0, v16, s[62:63]
	v_addc_co_u32_e64 v16, s[64:65], 0, v16, s[64:65]
	v_addc_co_u32_e64 v16, s[66:67], 0, v16, s[66:67]
	v_addc_co_u32_e64 v16, s[68:69], 0, v16, s[68:69]
	v_addc_co_u32_e64 v16, s[70:71], 0, v16, s[70:71]
	v_addc_co_u32_e64 v16, s[72:73], 0, v16, s[72:73]
	v_cmp_le_u32_e64 s[38:39], s8, v222
	v_cmp_le_u32_e64 s[42:43], s8, v221
	v_cmp_le_u32_e64 s[62:63], s8, v220
	v_cmp_le_u32_e64 s[64:65], s8, v219
	v_cmp_le_u32_e64 s[66:67], s8, v218
	v_cmp_le_u32_e64 s[68:69], s8, v217
	v_cmp_le_u32_e64 s[70:71], s8, v215
	v_cmp_le_u32_e64 s[72:73], s8, v216
	v_addc_co_u32_e64 v16, s[38:39], 0, v16, s[38:39]
	v_addc_co_u32_e64 v16, s[42:43], 0, v16, s[42:43]
	v_addc_co_u32_e64 v16, s[62:63], 0, v16, s[62:63]
	v_addc_co_u32_e64 v16, s[64:65], 0, v16, s[64:65]
	v_addc_co_u32_e64 v16, s[66:67], 0, v16, s[66:67]
	v_addc_co_u32_e64 v16, s[68:69], 0, v16, s[68:69]
	v_addc_co_u32_e64 v16, s[70:71], 0, v16, s[70:71]
	v_addc_co_u32_e64 v16, s[72:73], 0, v16, s[72:73]
	v_cmp_le_u32_e64 s[38:39], s8, v214
	v_cmp_le_u32_e64 s[42:43], s8, v213
	v_cmp_le_u32_e64 s[62:63], s8, v212
	v_cmp_le_u32_e64 s[64:65], s8, v211
	v_cmp_le_u32_e64 s[66:67], s8, v210
	v_cmp_le_u32_e64 s[68:69], s8, v207
	v_cmp_le_u32_e64 s[70:71], s8, v194
	v_cmp_le_u32_e64 s[72:73], s8, v195
	v_addc_co_u32_e64 v16, s[38:39], 0, v16, s[38:39]
	v_addc_co_u32_e64 v16, s[42:43], 0, v16, s[42:43]
	v_addc_co_u32_e64 v16, s[62:63], 0, v16, s[62:63]
	v_addc_co_u32_e64 v16, s[64:65], 0, v16, s[64:65]
	v_addc_co_u32_e64 v16, s[66:67], 0, v16, s[66:67]
	v_addc_co_u32_e64 v16, s[68:69], 0, v16, s[68:69]
	v_addc_co_u32_e64 v16, s[70:71], 0, v16, s[70:71]
	v_addc_co_u32_e64 v16, s[72:73], 0, v16, s[72:73]
	v_cmp_le_u32_e64 s[38:39], s8, v193
	v_cmp_le_u32_e64 s[42:43], s8, v192
	v_cmp_le_u32_e64 s[62:63], s8, v191
	v_cmp_le_u32_e64 s[64:65], s8, v190
	v_cmp_le_u32_e64 s[66:67], s8, v189
	v_cmp_le_u32_e64 s[68:69], s8, v188
	v_cmp_le_u32_e64 s[70:71], s8, v186
	v_cmp_le_u32_e64 s[72:73], s8, v187
	v_addc_co_u32_e64 v16, s[38:39], 0, v16, s[38:39]
	v_addc_co_u32_e64 v16, s[42:43], 0, v16, s[42:43]
	v_addc_co_u32_e64 v16, s[62:63], 0, v16, s[62:63]
	v_addc_co_u32_e64 v16, s[64:65], 0, v16, s[64:65]
	v_addc_co_u32_e64 v16, s[66:67], 0, v16, s[66:67]
	v_addc_co_u32_e64 v16, s[68:69], 0, v16, s[68:69]
	v_addc_co_u32_e64 v16, s[70:71], 0, v16, s[70:71]
	v_addc_co_u32_e64 v16, s[72:73], 0, v16, s[72:73]
	v_cmp_le_u32_e64 s[38:39], s8, v185
	v_cmp_le_u32_e64 s[42:43], s8, v184
	v_cmp_le_u32_e64 s[62:63], s8, v183
	v_cmp_le_u32_e64 s[64:65], s8, v182
	v_cmp_le_u32_e64 s[66:67], s8, v181
	v_cmp_le_u32_e64 s[68:69], s8, v180
	v_cmp_le_u32_e64 s[70:71], s8, v178
	v_cmp_le_u32_e64 s[72:73], s8, v179
	v_addc_co_u32_e64 v16, s[38:39], 0, v16, s[38:39]
	v_addc_co_u32_e64 v16, s[42:43], 0, v16, s[42:43]
	v_addc_co_u32_e64 v16, s[62:63], 0, v16, s[62:63]
	v_addc_co_u32_e64 v16, s[64:65], 0, v16, s[64:65]
	v_addc_co_u32_e64 v16, s[66:67], 0, v16, s[66:67]
	v_addc_co_u32_e64 v16, s[68:69], 0, v16, s[68:69]
	v_addc_co_u32_e64 v16, s[70:71], 0, v16, s[70:71]
	v_addc_co_u32_e64 v16, s[72:73], 0, v16, s[72:73]
	v_cmp_le_u32_e64 s[38:39], s8, v177
	v_cmp_le_u32_e64 s[42:43], s8, v176
	v_cmp_le_u32_e64 s[62:63], s8, v175
	v_cmp_le_u32_e64 s[64:65], s8, v174
	v_cmp_le_u32_e64 s[66:67], s8, v173
	v_cmp_le_u32_e64 s[68:69], s8, v172
	v_cmp_le_u32_e64 s[70:71], s8, v115
	v_cmp_le_u32_e64 s[72:73], s8, v243
	v_addc_co_u32_e64 v16, s[38:39], 0, v16, s[38:39]
	v_addc_co_u32_e64 v16, s[42:43], 0, v16, s[42:43]
	v_addc_co_u32_e64 v16, s[62:63], 0, v16, s[62:63]
	v_addc_co_u32_e64 v16, s[64:65], 0, v16, s[64:65]
	v_addc_co_u32_e64 v16, s[66:67], 0, v16, s[66:67]
	v_addc_co_u32_e64 v16, s[68:69], 0, v16, s[68:69]
	v_addc_co_u32_e64 v16, s[70:71], 0, v16, s[70:71]
	v_addc_co_u32_e64 v16, s[72:73], 0, v16, s[72:73]
	v_cmp_le_u32_e64 s[38:39], s8, v242
	v_cmp_le_u32_e64 s[42:43], s8, v241
	v_cmp_le_u32_e64 s[62:63], s8, v240
	v_cmp_le_u32_e64 s[64:65], s8, v171
	v_cmp_le_u32_e64 s[66:67], s8, v170
	v_cmp_le_u32_e64 s[68:69], s8, v169
	v_cmp_le_u32_e64 s[70:71], s8, v168
	v_addc_co_u32_e64 v16, s[38:39], 0, v16, s[38:39]
	v_addc_co_u32_e64 v16, s[42:43], 0, v16, s[42:43]
	v_addc_co_u32_e64 v16, s[62:63], 0, v16, s[62:63]
	v_addc_co_u32_e64 v16, s[64:65], 0, v16, s[64:65]
	v_addc_co_u32_e64 v16, s[66:67], 0, v16, s[66:67]
	v_addc_co_u32_e64 v16, s[68:69], 0, v16, s[68:69]
	v_addc_co_u32_e64 v16, s[70:71], 0, v16, s[70:71]
	v_cmp_le_u32_e32 vcc, s8, v239
	v_add_u32_e32 v167, -1, v252
	s_nop 0
	v_addc_co_u32_e64 v16, s[0:1], 0, v16, vcc
	v_add_u32_e32 v239, -2, v252
	v_and_b32_e32 v166, 64, v252
	v_cmp_lt_i32_e64 s[0:1], v167, v166
	s_nop 1
	v_cndmask_b32_e64 v167, v167, v252, s[0:1]
	v_lshlrev_b32_e32 v167, 2, v167
	ds_bpermute_b32 v167, v167, v16
	v_cmp_ne_u32_e64 s[0:1], 0, v114
	s_waitcnt lgkmcnt(0)
; __device__ __forceinline__ void select_group(unsigned char* ws, int r0, const bf16_t* __restrict__ kib, int n, float* sc, SelPre& pre, int nr0, const bf16_t* __restrict__ nkib, int nn) {
;     ...
;       int incl = myc;
; #pragma unroll
;       for (int d = 1; d < 64; d <<= 1) {
;         const int t = __shfl_up(incl, d);
;         incl += (lane >= d) ? t : 0;
;       }
;       int pos = incl - myc;
; #pragma unroll
;       for (int blk = 0; blk < 8; ++blk) {
;         if (blk * 8 < nreg) {
; #pragma unroll
;           for (int i = blk * 8; i < blk * 8 + 8; ++i) {
;             if (x[i] >= tau2) { selrow[pos] = (unsigned short)(i * 64 + lane); ++pos; }
	s_nop 0
	v_cndmask_b32_e64 v167, 0, v167, s[0:1]
	v_cmp_lt_i32_e64 s[0:1], v239, v166
	v_add_u32_e32 v167, v167, v16
	s_nop 0
	v_cndmask_b32_e64 v239, v239, v252, s[0:1]
	v_lshlrev_b32_e32 v239, 2, v239
	ds_bpermute_b32 v239, v239, v167
	v_cmp_lt_u32_e64 s[0:1], 1, v114
	s_waitcnt lgkmcnt(0)
	s_nop 0
	v_cndmask_b32_e64 v239, 0, v239, s[0:1]
	v_add_u32_e32 v167, v239, v167
	v_add_u32_e32 v239, -4, v252
	v_cmp_lt_i32_e64 s[0:1], v239, v166
	s_nop 1
	v_cndmask_b32_e64 v239, v239, v252, s[0:1]
	v_lshlrev_b32_e32 v239, 2, v239
	ds_bpermute_b32 v239, v239, v167
	v_cmp_lt_u32_e64 s[0:1], 3, v114
	s_waitcnt lgkmcnt(0)
	s_nop 0
	v_cndmask_b32_e64 v239, 0, v239, s[0:1]
	v_add_u32_e32 v167, v239, v167
	v_add_u32_e32 v239, -8, v252
	v_cmp_lt_i32_e64 s[0:1], v239, v166
	s_nop 1
	v_cndmask_b32_e64 v239, v239, v252, s[0:1]
	v_lshlrev_b32_e32 v239, 2, v239
	ds_bpermute_b32 v239, v239, v167
	v_cmp_lt_u32_e64 s[0:1], 7, v114
	s_waitcnt lgkmcnt(0)
	s_nop 0
	v_cndmask_b32_e64 v239, 0, v239, s[0:1]
	v_add_u32_e32 v167, v239, v167
	v_add_u32_e32 v239, -16, v252
	v_cmp_lt_i32_e64 s[0:1], v239, v166
	s_nop 1
	v_cndmask_b32_e64 v239, v239, v252, s[0:1]
	v_lshlrev_b32_e32 v239, 2, v239
	ds_bpermute_b32 v239, v239, v167
	v_cmp_lt_u32_e64 s[0:1], 15, v114
	s_waitcnt lgkmcnt(0)
	s_nop 0
	v_cndmask_b32_e64 v239, 0, v239, s[0:1]
	v_add_u32_e32 v167, v239, v167
	v_subrev_u32_e32 v239, 32, v252
	v_cmp_lt_i32_e64 s[0:1], v239, v166
	v_sub_u32_e32 v16, v167, v16
	s_nop 0
	v_cndmask_b32_e64 v166, v239, v252, s[0:1]
	v_lshlrev_b32_e32 v166, 2, v166
	ds_bpermute_b32 v166, v166, v167
	v_cmp_lt_u32_e64 s[0:1], 31, v114
	s_waitcnt lgkmcnt(0)
	s_nop 0
	v_cndmask_b32_e64 v166, 0, v166, s[0:1]
	v_add_u32_e32 v166, v16, v166
	s_and_saveexec_b64 s[0:1], vcc
	s_cbranch_execz .LBB0_3264
	v_add_u32_e32 v16, 1, v166
	v_lshl_add_u32 v167, v166, 1, s100
	ds_write_b16 v167, v114
	v_mov_b32_e32 v166, v16
	s_or_b64 exec, exec, s[0:1]
	v_cmp_le_u32_e32 vcc, s8, v238
	s_and_saveexec_b64 s[0:1], vcc
	s_cbranch_execnz .LBB0_3265
